# attention: the next item's Q rows, rope rows and first K/V tile are all prefetched at the start of the epilogue; tile loop unchanged and at the same code phase
# speedup vs baseline: 1.0026x; 1.0026x over previous
; __device__ __forceinline__ void attn_body(const bf16_t* __restrict__ Qb, const bf16_t* __restrict__ KVh, const bf16_t* __restrict__ KR, const float* __restrict__ ropeq,
;                                           bf16_t* __restrict__ Ob, int seq, char* lds, const int tid) {
;     ...
;     { const bf16_t* Qw = Qb + (size_t)(wid * QBLK + r32) * NQ + hi * 8;
; #pragma unroll
;       for (int d0 = 0; d0 < 4; ++d0) qr[d0] = *reinterpret_cast<const bf16x8*>(Qw + d0 * 16);
;       const u32x4 w1 = *reinterpret_cast<const u32x4*>(Qw + 64), w2 = *reinterpret_cast<const u32x4*>(Qw + 80);
;       float x1[8], x2[8]; unpack8(w1, x1); unpack8(w2, x2);
;       const float* rp = ropeq + (size_t)(wid * QBLK + r32) * 32 + hi * 8;
.LA_pf0:
	v_add_u32_e32 v247, 0x20000, v243
	global_load_dwordx4 v[228:231], v243, s[28:29]
	global_load_dwordx4 v[130:133], v247, s[28:29]
	global_load_dwordx4 v[248:251], v244, s[44:45]
	s_add_u32 s28, s28, 0x40000
	s_addc_u32 s29, s29, 0
	s_add_u32 s44, s44, 0x1000
	s_addc_u32 s45, s45, 0
	v_and_b32_e32 v245, 31, v211
	v_lshrrev_b32_e32 v246, 5, v211
	v_mul_u32_u24_e32 v247, 0xc00, v245
	v_lshl_add_u32 v247, v246, 4, v247
	v_lshlrev_b32_e32 v202, 7, v245
	v_lshl_add_u32 v202, v246, 5, v202
	global_load_dwordx4 v[142:145], v247, s[30:31] offset:0
	global_load_dwordx4 v[146:149], v247, s[30:31] offset:32
	global_load_dwordx4 v[150:153], v247, s[30:31] offset:64
	global_load_dwordx4 v[154:157], v247, s[30:31] offset:96
	global_load_dwordx4 v[158:161], v247, s[30:31] offset:128
	global_load_dwordx4 v[162:165], v247, s[30:31] offset:160
	global_load_dwordx4 v[66:69], v202, s[40:41] offset:0
	global_load_dwordx4 v[70:73], v202, s[40:41] offset:16
	global_load_dwordx4 v[74:77], v202, s[40:41] offset:64
	global_load_dwordx4 v[78:81], v202, s[40:41] offset:80
	v_add_u32_e32 v247, 0x18000, v247
	v_add_u32_e32 v202, 0x1000, v202
	global_load_dwordx4 v[166:169], v247, s[30:31] offset:0
	global_load_dwordx4 v[170:173], v247, s[30:31] offset:32
	global_load_dwordx4 v[174:177], v247, s[30:31] offset:64
	global_load_dwordx4 v[178:181], v247, s[30:31] offset:96
	global_load_dwordx4 v[182:185], v247, s[30:31] offset:128
	global_load_dwordx4 v[186:189], v247, s[30:31] offset:160
	global_load_dwordx4 v[98:101], v202, s[40:41] offset:0
	global_load_dwordx4 v[102:105], v202, s[40:41] offset:16
	global_load_dwordx4 v[106:109], v202, s[40:41] offset:64
	global_load_dwordx4 v[110:113], v202, s[40:41] offset:80
; __device__ __forceinline__ unsigned pk2(float lo, float hi) { return f2bf(lo) | (f2bf(hi) << 16); }
; #define SLOAD(i, k0) do { sr_[i].a0 = *reinterpret_cast<const bf16x8*>(&KVh[(size_t)((k0) + sr) * NKV + c16 * 8]); sr_[i].a1 = *reinterpret_cast<const bf16x8*>(&KVh[(size_t)((k0) + 32 + sr) * NKV + c16 * 8]); \
;     sr_[i].rr = *reinterpret_cast<const bf16x8*>(&KR[(size_t)((k0) + rkey) * 32 + rch * 8]); } while (0)
; #define SWRITE(b, i) do { if (isK) { *(bf16x8*)(K_lds + (b) * SHM_K + kst0) = sr_[i].a0; *(bf16x8*)(K_lds + (b) * SHM_K + kst1) = sr_[i].a1; } \
;     else { *(bf16x8*)(V_lds + (b) * SHM_V + vst0) = sr_[i].a0; *(bf16x8*)(V_lds + (b) * SHM_V + vst1) = sr_[i].a1; } \
;     if (rwr) *(bf16x8*)(K_lds + (b) * SHM_K + rst) = sr_[i].rr; } while (0)
; __device__ __forceinline__ void attn_body(const bf16_t* __restrict__ Qb, const bf16_t* __restrict__ KVh, const bf16_t* __restrict__ KR, const float* __restrict__ ropeq,
;                                           bf16_t* __restrict__ Ob, int seq, char* lds, const int tid) {
;     ...
;     { const bf16_t* Qw = Qb + (size_t)(wid * QBLK + r32) * NQ + hi * 8;
; #pragma unroll
;       for (int d0 = 0; d0 < 4; ++d0) qr[d0] = *reinterpret_cast<const bf16x8*>(Qw + d0 * 16);
;       const u32x4 w1 = *reinterpret_cast<const u32x4*>(Qw + 64), w2 = *reinterpret_cast<const u32x4*>(Qw + 80);
;       float x1[8], x2[8]; unpack8(w1, x1); unpack8(w2, x2);
;       const float* rp = ropeq + (size_t)(wid * QBLK + r32) * 32 + hi * 8;
;       float y1[8], y2[8];
; #pragma unroll
;       for (int e = 0; e < 8; ++e) { const float c = rp[e], s = rp[16 + e]; y1[e] = x1[e] * c - x2[e] * s; y2[e] = x1[e] * s + x2[e] * c; }
;       u32x4 o1 = {pk2(y1[0], y1[1]), pk2(y1[2], y1[3]), pk2(y1[4], y1[5]), pk2(y1[6], y1[7])};
;       u32x4 o2 = {pk2(y2[0], y2[1]), pk2(y2[2], y2[3]), pk2(y2[4], y2[5]), pk2(y2[6], y2[7])};
;       qr[4] = *reinterpret_cast<bf16x8*>(&o1); qr[5] = *reinterpret_cast<bf16x8*>(&o2); }
;     ...
;     SLOAD(SE, 0); asm volatile("s_waitcnt vmcnt(0)" ::: "memory"); SWRITE(0, SE); __syncthreads();
.LA_pf1:
	v_mov_b32_e32 v141, 0xf149f2ca
	v_mov_b32_e32 v254, 0
	v_mov_b32_e32 v64, 0
	v_mov_b32_e32 v0, 0
	v_mov_b32_e32 v1, 0
	v_mov_b32_e32 v2, 0
	v_mov_b32_e32 v3, 0
	v_mov_b32_e32 v4, 0
	v_mov_b32_e32 v5, 0
	v_mov_b32_e32 v6, 0
	v_mov_b32_e32 v7, 0
	v_mov_b32_e32 v8, 0
	v_mov_b32_e32 v9, 0
	v_mov_b32_e32 v10, 0
	v_mov_b32_e32 v11, 0
	v_mov_b32_e32 v12, 0
	v_mov_b32_e32 v13, 0
	v_mov_b32_e32 v14, 0
	v_mov_b32_e32 v15, 0
	v_mov_b32_e32 v16, 0
	v_mov_b32_e32 v17, 0
	v_mov_b32_e32 v18, 0
	v_mov_b32_e32 v19, 0
	v_mov_b32_e32 v20, 0
	v_mov_b32_e32 v21, 0
	v_mov_b32_e32 v22, 0
	v_mov_b32_e32 v23, 0
	v_mov_b32_e32 v24, 0
	v_mov_b32_e32 v25, 0
	v_mov_b32_e32 v26, 0
	v_mov_b32_e32 v27, 0
	v_mov_b32_e32 v28, 0
	v_mov_b32_e32 v29, 0
	v_mov_b32_e32 v30, 0
	v_mov_b32_e32 v31, 0
	v_mov_b32_e32 v139, 0xf149f2ca
	v_mov_b32_e32 v255, 0
	v_mov_b32_e32 v134, 0
	v_mov_b32_e32 v32, 0
	v_mov_b32_e32 v33, 0
	v_mov_b32_e32 v34, 0
	v_mov_b32_e32 v35, 0
	v_mov_b32_e32 v36, 0
	v_mov_b32_e32 v37, 0
	v_mov_b32_e32 v38, 0
	v_mov_b32_e32 v39, 0
	v_mov_b32_e32 v40, 0
	v_mov_b32_e32 v41, 0
	v_mov_b32_e32 v42, 0
	v_mov_b32_e32 v43, 0
	v_mov_b32_e32 v44, 0
	v_mov_b32_e32 v45, 0
	v_mov_b32_e32 v46, 0
	v_mov_b32_e32 v47, 0
	v_mov_b32_e32 v48, 0
	v_mov_b32_e32 v49, 0
	v_mov_b32_e32 v50, 0
	v_mov_b32_e32 v51, 0
	v_mov_b32_e32 v52, 0
	v_mov_b32_e32 v53, 0
	v_mov_b32_e32 v54, 0
	v_mov_b32_e32 v55, 0
	v_mov_b32_e32 v56, 0
	v_mov_b32_e32 v57, 0
	v_mov_b32_e32 v58, 0
	v_mov_b32_e32 v59, 0
	v_mov_b32_e32 v60, 0
	v_mov_b32_e32 v61, 0
	v_mov_b32_e32 v62, 0
	v_mov_b32_e32 v63, 0
	s_waitcnt vmcnt(0)
	v_lshlrev_b32_e32 v82, 16, v158
	v_lshlrev_b32_e32 v83, 16, v162
	v_mul_f32_e32 v84, v83, v74
	v_fma_f32 v86, v82, v66, -v84
	v_mul_f32_e32 v84, v83, v66
	v_fma_f32 v87, v82, v74, v84
	v_and_b32_e32 v82, 0xffff0000, v158
	v_and_b32_e32 v83, 0xffff0000, v162
	v_mul_f32_e32 v84, v83, v75
	v_fma_f32 v85, v82, v67, -v84
	v_cvt_pk_bf16_f32 v158, v86, v85
	v_mul_f32_e32 v84, v83, v67
	v_fma_f32 v85, v82, v75, v84
	v_cvt_pk_bf16_f32 v162, v87, v85
	v_lshlrev_b32_e32 v82, 16, v159
	v_lshlrev_b32_e32 v83, 16, v163
	v_mul_f32_e32 v84, v83, v76
	v_fma_f32 v86, v82, v68, -v84
	v_mul_f32_e32 v84, v83, v68
	v_fma_f32 v87, v82, v76, v84
	v_and_b32_e32 v82, 0xffff0000, v159
	v_and_b32_e32 v83, 0xffff0000, v163
	v_mul_f32_e32 v84, v83, v77
	v_fma_f32 v85, v82, v69, -v84
	v_cvt_pk_bf16_f32 v159, v86, v85
	v_mul_f32_e32 v84, v83, v69
	v_fma_f32 v85, v82, v77, v84
	v_cvt_pk_bf16_f32 v163, v87, v85
	v_lshlrev_b32_e32 v82, 16, v160
	v_lshlrev_b32_e32 v83, 16, v164
	v_mul_f32_e32 v84, v83, v78
	v_fma_f32 v86, v82, v70, -v84
	v_mul_f32_e32 v84, v83, v70
	v_fma_f32 v87, v82, v78, v84
	v_and_b32_e32 v82, 0xffff0000, v160
	v_and_b32_e32 v83, 0xffff0000, v164
	v_mul_f32_e32 v84, v83, v79
	v_fma_f32 v85, v82, v71, -v84
	v_cvt_pk_bf16_f32 v160, v86, v85
	v_mul_f32_e32 v84, v83, v71
	v_fma_f32 v85, v82, v79, v84
	v_cvt_pk_bf16_f32 v164, v87, v85
	v_lshlrev_b32_e32 v82, 16, v161
	v_lshlrev_b32_e32 v83, 16, v165
	v_mul_f32_e32 v84, v83, v80
	v_fma_f32 v86, v82, v72, -v84
	v_mul_f32_e32 v84, v83, v72
	v_fma_f32 v87, v82, v80, v84
	v_and_b32_e32 v82, 0xffff0000, v161
	v_and_b32_e32 v83, 0xffff0000, v165
	v_mul_f32_e32 v84, v83, v81
	v_fma_f32 v85, v82, v73, -v84
	v_cvt_pk_bf16_f32 v161, v86, v85
	v_mul_f32_e32 v84, v83, v73
	v_fma_f32 v85, v82, v81, v84
	v_cvt_pk_bf16_f32 v165, v87, v85
	v_lshlrev_b32_e32 v114, 16, v182
	v_lshlrev_b32_e32 v115, 16, v186
	v_mul_f32_e32 v116, v115, v106
	v_fma_f32 v118, v114, v98, -v116
	v_mul_f32_e32 v116, v115, v98
	v_fma_f32 v119, v114, v106, v116
	v_and_b32_e32 v114, 0xffff0000, v182
	v_and_b32_e32 v115, 0xffff0000, v186
	v_mul_f32_e32 v116, v115, v107
	v_fma_f32 v117, v114, v99, -v116
	v_cvt_pk_bf16_f32 v182, v118, v117
	v_mul_f32_e32 v116, v115, v99
	v_fma_f32 v117, v114, v107, v116
	v_cvt_pk_bf16_f32 v186, v119, v117
	v_lshlrev_b32_e32 v114, 16, v183
	v_lshlrev_b32_e32 v115, 16, v187
	v_mul_f32_e32 v116, v115, v108
	v_fma_f32 v118, v114, v100, -v116
	v_mul_f32_e32 v116, v115, v100
	v_fma_f32 v119, v114, v108, v116
	v_and_b32_e32 v114, 0xffff0000, v183
	v_and_b32_e32 v115, 0xffff0000, v187
	v_mul_f32_e32 v116, v115, v109
	v_fma_f32 v117, v114, v101, -v116
	v_cvt_pk_bf16_f32 v183, v118, v117
	v_mul_f32_e32 v116, v115, v101
	v_fma_f32 v117, v114, v109, v116
	v_cvt_pk_bf16_f32 v187, v119, v117
	v_lshlrev_b32_e32 v114, 16, v184
	v_lshlrev_b32_e32 v115, 16, v188
	v_mul_f32_e32 v116, v115, v110
	v_fma_f32 v118, v114, v102, -v116
	v_mul_f32_e32 v116, v115, v102
	v_fma_f32 v119, v114, v110, v116
	v_and_b32_e32 v114, 0xffff0000, v184
	v_and_b32_e32 v115, 0xffff0000, v188
	v_mul_f32_e32 v116, v115, v111
	v_fma_f32 v117, v114, v103, -v116
	v_cvt_pk_bf16_f32 v184, v118, v117
	v_mul_f32_e32 v116, v115, v103
	v_fma_f32 v117, v114, v111, v116
	v_cvt_pk_bf16_f32 v188, v119, v117
	v_lshlrev_b32_e32 v114, 16, v185
	v_lshlrev_b32_e32 v115, 16, v189
	v_mul_f32_e32 v116, v115, v112
	v_fma_f32 v118, v114, v104, -v116
	v_mul_f32_e32 v116, v115, v104
	v_fma_f32 v119, v114, v112, v116
	v_and_b32_e32 v114, 0xffff0000, v185
	v_and_b32_e32 v115, 0xffff0000, v189
	v_mul_f32_e32 v116, v115, v113
	v_fma_f32 v117, v114, v105, -v116
	v_cvt_pk_bf16_f32 v185, v118, v117
	v_mul_f32_e32 v116, v115, v105
	v_fma_f32 v117, v114, v113, v116
	v_cvt_pk_bf16_f32 v189, v119, v117
	s_mov_b32 s18, 0
	s_mov_b32 s19, 0x4000
	s_mov_b32 s22, 0x8000
	s_mov_b32 s16, 0
	s_waitcnt vmcnt(0)
	v_add_u32_e32 v246, s18, v240
	v_add_u32_e32 v245, s18, v241
	ds_write_b128 v246, v[228:231]
	ds_write_b128 v245, v[130:133]
	s_cmp_eq_u64 s[2:3], 0
	s_cbranch_scc1 .LA_swp
	v_add_u32_e32 v245, s18, v242
	ds_write_b128 v245, v[248:251] offset:49152

; __device__ __forceinline__ void attn_body(const bf16_t* __restrict__ Qb, const bf16_t* __restrict__ KVh, const bf16_t* __restrict__ KR, const float* __restrict__ ropeq,
;                                           bf16_t* __restrict__ Ob, int seq, char* lds, const int tid) {
;     ...
;     { const bf16_t* Qw = Qb + (size_t)(wid * QBLK + r32) * NQ + hi * 8;
; #pragma unroll
;       for (int d0 = 0; d0 < 4; ++d0) qr[d0] = *reinterpret_cast<const bf16x8*>(Qw + d0 * 16);
;       const u32x4 w1 = *reinterpret_cast<const u32x4*>(Qw + 64), w2 = *reinterpret_cast<const u32x4*>(Qw + 80);
;       float x1[8], x2[8]; unpack8(w1, x1); unpack8(w2, x2);
;       const float* rp = ropeq + (size_t)(wid * QBLK + r32) * 32 + hi * 8;
; __device__ __forceinline__ void phase_attn(const Ctx& C, PP p, char* lds_generic) {
;     ...
;     for (int it = C.vcu; it < 2048; it += C.G) {
;         const int qb = it & 15, h = (it >> 4) & 15, b = it >> 8; const size_t t0 = (size_t)b * SEQ, q0 = t0 + qb * 256;
;         __syncthreads();
;         att::attn_body(Q + q0 * NQ + h * 96, KV + t0 * NKV + h * 128, KR + t0 * 32, rope + q0 * 32, O + q0 * DM + h * 64, SEQ, lds_generic, C.tid);
.LA_lexit:
	s_mov_b32 s47, 0
	s_add_i32 s13, s20, s85
	s_cmpk_lt_i32 s13, 0x400
	s_cbranch_scc0 .LA_npf
	s_mov_b32 s47, 1
	s_lshr_b32 s14, s13, 3
	s_and_b32 s14, s14, 15
	s_lshr_b32 s15, s13, 7
	s_and_b32 s13, s13, 7
	s_lshl_b32 s46, s15, 12
	s_lshl_b32 s13, s13, 9
	s_add_u32 s46, s46, s13
	s_lshl_b32 s13, s23, 6
	s_add_u32 s46, s46, s13
	s_mul_i32 s13, s46, 0xc00
	s_mul_i32 s30, s14, 0xc0
	s_add_u32 s13, s13, s30
	s_add_u32 s13, s13, 0xac00000
	s_add_u32 s30, s26, s13
	s_addc_u32 s31, s27, 0
	s_lshl_b32 s13, s46, 7
	s_add_u32 s13, s13, 0x100000
	s_add_u32 s40, s26, s13
	s_addc_u32 s41, s27, 0
	s_lshl_b32 s13, s15, 24
	s_lshl_b32 s14, s14, 8
	s_add_u32 s13, s13, s14
	s_add_u32 s13, s13, 0x10c00000
	s_add_u32 s28, s26, s13
	s_addc_u32 s29, s27, 0
	s_lshl_b32 s13, s15, 18
	s_add_u32 s13, s13, 0x1d400000
	s_add_u32 s44, s26, s13
	s_addc_u32 s45, s27, 0
	v_add_u32_e32 v247, 0x20000, v243
	global_load_dwordx4 v[228:231], v243, s[28:29]
	global_load_dwordx4 v[130:133], v247, s[28:29]
	global_load_dwordx4 v[248:251], v244, s[44:45]
	s_add_u32 s28, s28, 0x40000
	s_addc_u32 s29, s29, 0
	s_add_u32 s44, s44, 0x1000
	s_addc_u32 s45, s45, 0
	v_and_b32_e32 v245, 31, v211
	v_lshrrev_b32_e32 v246, 5, v211
	v_mul_u32_u24_e32 v128, 0xc00, v245
	v_lshl_add_u32 v128, v246, 4, v128
	v_lshlrev_b32_e32 v129, 7, v245
	v_lshl_add_u32 v129, v246, 5, v129
	global_load_dwordx4 v[142:145], v128, s[30:31] offset:0
	global_load_dwordx4 v[146:149], v128, s[30:31] offset:32
	global_load_dwordx4 v[150:153], v128, s[30:31] offset:64
	global_load_dwordx4 v[154:157], v128, s[30:31] offset:96
	global_load_dwordx4 v[158:161], v128, s[30:31] offset:128
	global_load_dwordx4 v[162:165], v128, s[30:31] offset:160
	global_load_dwordx4 v[66:69], v129, s[40:41] offset:0
	global_load_dwordx4 v[70:73], v129, s[40:41] offset:16
	global_load_dwordx4 v[74:77], v129, s[40:41] offset:64
	global_load_dwordx4 v[78:81], v129, s[40:41] offset:80
	v_add_u32_e32 v128, 0x18000, v128
	v_add_u32_e32 v129, 0x1000, v129
	global_load_dwordx4 v[166:169], v128, s[30:31] offset:0
	global_load_dwordx4 v[170:173], v128, s[30:31] offset:32
	global_load_dwordx4 v[174:177], v128, s[30:31] offset:64
	global_load_dwordx4 v[178:181], v128, s[30:31] offset:96
	global_load_dwordx4 v[182:185], v128, s[30:31] offset:128
	global_load_dwordx4 v[186:189], v128, s[30:31] offset:160
	global_load_dwordx4 v[98:101], v129, s[40:41] offset:0
	global_load_dwordx4 v[102:105], v129, s[40:41] offset:16
	global_load_dwordx4 v[106:109], v129, s[40:41] offset:64
	global_load_dwordx4 v[110:113], v129, s[40:41] offset:80
